# second measurement of v19 (static priority raise in P3 and rmsnorm phases on top of the stacked version)
# speedup vs baseline: 1.0311x; 1.0029x over previous
; __global__ void __launch_bounds__(512, 2) fwd_megakernel(Params P) {
;     ...
;         rmsnorm_rows<true>(xin, P.in[I_N1G] + l * DM, hbuf, P, l, lds, gw, NGW, lane);
.LBB0_76:
	v_readlane_b32 s4, v254, 9
	v_mov_b32_e32 v18, v180
	s_mov_b32 s12, s4
	s_waitcnt lgkmcnt(0)
	s_barrier
	v_readfirstlane_b32 s3, v180
	s_nop 3
	s_cmp_ge_u32 s3, 0x100
	s_cbranch_scc0 .Lprio_p1
	s_setprio 1
.Lprio_p1:
	s_and_b32 s3, s12, 7
	v_readfirstlane_b32 s13, v18
	v_readlane_b32 s14, v254, 0
	s_cmp_lg_u32 s3, 0
	v_readlane_b32 s5, v254, 10
	s_cbranch_scc1 .LBB0_78
	s_ashr_i32 s4, s14, 31
	s_lshr_b32 s4, s4, 29
	s_add_i32 s4, s14, s4
	s_ashr_i32 s5, s4, 3
	s_and_b32 s4, s4, -8
	s_ashr_i32 s3, s12, 3
	s_sub_i32 s4, s14, s4
	s_mul_i32 s3, s4, s3
	s_add_i32 s14, s3, s5
